# v1 + L1 out-proj fused epilogue: x1 residual loads of all 8 row groups issued up front
# baseline (speedup 1.0000x reference)
.LBB0_1155:
	s_lshl_b32 s1, s8, 8
	v_add_u32_e32 v132, s1, v164
	v_ashrrev_i32_e32 v140, 11, v132
	s_lshl_b32 s2, s3, 5
	v_lshlrev_b32_e32 v165, 3, v150
	v_mul_i32_i24_e32 v142, 0xc00, v140
	s_lshl_b32 s0, s43, 8
	v_or_b32_e32 v130, s2, v165
	v_ashrrev_i32_e32 v133, 31, v132
	v_ashrrev_i32_e32 v143, 31, v142
	v_or_b32_e32 v130, s0, v130
	v_lshlrev_b64 v[134:135], 11, v[132:133]
	v_lshl_add_u64 v[142:143], v[142:143], 2, s[56:57]
	s_mov_b64 s[4:5], 0x2000
	v_lshl_add_u64 v[134:135], s[26:27], 0, v[134:135]
	v_ashrrev_i32_e32 v131, 31, v130
	v_lshl_add_u64 v[148:149], v[142:143], 0, s[4:5]
	v_lshl_add_u64 v[138:139], v[130:131], 1, v[134:135]
	v_lshl_add_u64 v[142:143], v[130:131], 2, v[148:149]
	s_waitcnt vmcnt(0)
	s_barrier
	global_load_dwordx4 v[134:137], v[138:139], off
	s_lshl_b32 s3, s3, 2
	global_load_dwordx4 v[138:141], v[138:139], off offset:256
	s_nop 0
	global_load_dwordx4 v[144:147], v[142:143], off offset:16
	global_load_dwordx4 v[152:155], v[142:143], off
	v_or_b32_e32 v142, 0x80, v130
	v_ashrrev_i32_e32 v143, 31, v142
	v_lshl_add_u64 v[148:149], v[142:143], 2, v[148:149]
	global_load_dwordx4 v[156:159], v[148:149], off
	global_load_dwordx4 v[160:163], v[148:149], off offset:16
	v_or_b32_e32 v246, 16, v164
	v_add_u32_e32 v246, s1, v246
	v_ashrrev_i32_e32 v247, 31, v246
	v_lshlrev_b64 v[246:247], 11, v[246:247]
	v_lshl_add_u64 v[246:247], s[26:27], 0, v[246:247]
	v_lshl_add_u64 v[246:247], v[130:131], 1, v[246:247]
	global_load_dwordx4 v[190:193], v[246:247], off
	global_load_dwordx4 v[194:197], v[246:247], off offset:256
	v_or_b32_e32 v246, 32, v164
	v_add_u32_e32 v246, s1, v246
	v_ashrrev_i32_e32 v247, 31, v246
	v_lshlrev_b64 v[246:247], 11, v[246:247]
	v_lshl_add_u64 v[246:247], s[26:27], 0, v[246:247]
	v_lshl_add_u64 v[246:247], v[130:131], 1, v[246:247]
	global_load_dwordx4 v[198:201], v[246:247], off
	global_load_dwordx4 v[202:205], v[246:247], off offset:256
	v_or_b32_e32 v246, 48, v164
	v_add_u32_e32 v246, s1, v246
	v_ashrrev_i32_e32 v247, 31, v246
	v_lshlrev_b64 v[246:247], 11, v[246:247]
	v_lshl_add_u64 v[246:247], s[26:27], 0, v[246:247]
	v_lshl_add_u64 v[246:247], v[130:131], 1, v[246:247]
	global_load_dwordx4 v[206:209], v[246:247], off
	global_load_dwordx4 v[210:213], v[246:247], off offset:256
	v_add_u32_e32 v246, 0x80, v164
	v_add_u32_e32 v246, s1, v246
	v_ashrrev_i32_e32 v247, 31, v246
	v_lshlrev_b64 v[246:247], 11, v[246:247]
	v_lshl_add_u64 v[246:247], s[26:27], 0, v[246:247]
	v_lshl_add_u64 v[246:247], v[130:131], 1, v[246:247]
	global_load_dwordx4 v[214:217], v[246:247], off
	global_load_dwordx4 v[218:221], v[246:247], off offset:256
	v_add_u32_e32 v246, 0x90, v164
	v_add_u32_e32 v246, s1, v246
	v_ashrrev_i32_e32 v247, 31, v246
	v_lshlrev_b64 v[246:247], 11, v[246:247]
	v_lshl_add_u64 v[246:247], s[26:27], 0, v[246:247]
	v_lshl_add_u64 v[246:247], v[130:131], 1, v[246:247]
	global_load_dwordx4 v[222:225], v[246:247], off
	global_load_dwordx4 v[226:229], v[246:247], off offset:256
	v_add_u32_e32 v246, 0xa0, v164
	v_add_u32_e32 v246, s1, v246
	v_ashrrev_i32_e32 v247, 31, v246
	v_lshlrev_b64 v[246:247], 11, v[246:247]
	v_lshl_add_u64 v[246:247], s[26:27], 0, v[246:247]
	v_lshl_add_u64 v[246:247], v[130:131], 1, v[246:247]
	global_load_dwordx4 v[230:233], v[246:247], off
	global_load_dwordx4 v[234:237], v[246:247], off offset:256
	v_add_u32_e32 v246, 0xb0, v164
	v_add_u32_e32 v246, s1, v246
	v_ashrrev_i32_e32 v247, 31, v246
	v_lshlrev_b64 v[246:247], 11, v[246:247]
	v_lshl_add_u64 v[246:247], s[26:27], 0, v[246:247]
	v_lshl_add_u64 v[246:247], v[130:131], 1, v[246:247]
	global_load_dwordx4 v[238:241], v[246:247], off
	global_load_dwordx4 v[242:245], v[246:247], off offset:256
	v_mbcnt_lo_u32_b32 v148, -1, 0
	v_mbcnt_hi_u32_b32 v151, -1, v148
	v_and_b32_e32 v149, 64, v151
	v_xor_b32_e32 v148, 16, v151
	v_add_u32_e32 v167, 64, v149
	v_cmp_lt_i32_e32 vcc, v148, v167
	s_add_i32 s3, s3, 0
	s_waitcnt vmcnt(14)
	v_and_b32_e32 v149, 0xffff0000, v134
	v_cndmask_b32_e32 v148, v151, v148, vcc
	v_lshlrev_b32_e32 v166, 2, v148
	v_lshlrev_b32_e32 v148, 16, v134
	v_lshlrev_b32_e32 v134, 16, v135
	v_and_b32_e32 v135, 0xffff0000, v135
	v_lshlrev_b32_e32 v168, 16, v136
	v_and_b32_e32 v169, 0xffff0000, v136
	v_lshlrev_b32_e32 v136, 16, v137
	v_and_b32_e32 v137, 0xffff0000, v137
	v_lshlrev_b32_e32 v170, 16, v138
	v_and_b32_e32 v171, 0xffff0000, v138
	v_lshlrev_b32_e32 v138, 16, v139
	v_and_b32_e32 v139, 0xffff0000, v139
	v_lshlrev_b32_e32 v172, 16, v140
	v_and_b32_e32 v173, 0xffff0000, v140
	v_lshlrev_b32_e32 v140, 16, v141
	v_and_b32_e32 v141, 0xffff0000, v141
	v_pk_fma_f32 v[128:129], v[128:129], v[154:155], v[134:135]
	v_pk_fma_f32 v[126:127], v[126:127], v[152:153], v[148:149]
	v_pk_fma_f32 v[124:125], v[124:125], v[146:147], v[136:137]
	v_pk_fma_f32 v[122:123], v[122:123], v[144:145], v[168:169]
	v_pk_fma_f32 v[120:121], v[120:121], v[158:159], v[138:139]
	v_pk_fma_f32 v[118:119], v[118:119], v[156:157], v[170:171]
	v_pk_fma_f32 v[116:117], v[116:117], v[162:163], v[140:141]
	v_pk_fma_f32 v[114:115], v[114:115], v[160:161], v[172:173]
	v_mul_f32_e32 v134, v127, v127
	v_mul_f32_e32 v135, v129, v129
	v_mul_f32_e32 v136, v123, v123
	v_mul_f32_e32 v137, v125, v125
	v_mul_f32_e32 v138, v119, v119
	v_mul_f32_e32 v139, v121, v121
	v_mul_f32_e32 v140, v115, v115
	v_mul_f32_e32 v141, v117, v117
	v_fmac_f32_e32 v134, v126, v126
	v_fmac_f32_e32 v135, v128, v128
	v_fmac_f32_e32 v136, v122, v122
	v_fmac_f32_e32 v137, v124, v124
	v_fmac_f32_e32 v138, v118, v118
	v_fmac_f32_e32 v139, v120, v120
	v_fmac_f32_e32 v140, v114, v114
	v_fmac_f32_e32 v141, v116, v116
	v_add_f32_e32 v134, v134, v135
	v_add_f32_e32 v135, v136, v137
	v_add_f32_e32 v136, v138, v139
	v_add_f32_e32 v137, v140, v141
	v_add_f32_e32 v134, v134, v135
	v_add_f32_e32 v135, v136, v137
	v_add_f32_e32 v134, v134, v135
	ds_bpermute_b32 v135, v166, v134
	v_xor_b32_e32 v136, 32, v151
	v_cmp_lt_i32_e32 vcc, v136, v167
	s_waitcnt lgkmcnt(0)
	v_add_f32_e32 v134, v134, v135
	v_cndmask_b32_e32 v136, v151, v136, vcc
	v_lshlrev_b32_e32 v167, 2, v136
	ds_bpermute_b32 v135, v167, v134
	v_cmp_eq_u32_e32 vcc, 0, v150
	s_and_saveexec_b64 s[8:9], vcc
	s_cbranch_execz .LBB0_1157
	v_lshl_add_u32 v136, v164, 4, s3
	s_waitcnt lgkmcnt(0)
	v_add_f32_e32 v134, v134, v135
	ds_write_b32 v136, v134
.LBB0_1157:
	s_or_b64 exec, exec, s[8:9]
	v_or_b32_e32 v136, 16, v164
	v_add_u32_e32 v134, s1, v136
	v_ashrrev_i32_e32 v137, 11, v134
	s_waitcnt lgkmcnt(0)
	v_ashrrev_i32_e32 v135, 31, v134
	v_mul_i32_i24_e32 v148, 0xc00, v137
	v_lshlrev_b64 v[138:139], 11, v[134:135]
	v_ashrrev_i32_e32 v149, 31, v148
	v_lshl_add_u64 v[138:139], s[26:27], 0, v[138:139]
	v_lshl_add_u64 v[148:149], v[148:149], 2, s[56:57]
	v_lshl_add_u64 v[144:145], v[130:131], 1, v[138:139]
	v_lshl_add_u64 v[156:157], v[148:149], 0, s[4:5]
	s_nop 0
	v_lshl_add_u64 v[152:153], v[130:131], 2, v[156:157]
	v_lshl_add_u64 v[160:161], v[142:143], 2, v[156:157]
	global_load_dwordx4 v[148:151], v[152:153], off
	s_nop 0
	global_load_dwordx4 v[152:155], v[152:153], off offset:16
	s_nop 0
	global_load_dwordx4 v[156:159], v[160:161], off
	s_nop 0
	global_load_dwordx4 v[160:163], v[160:161], off offset:16
	s_waitcnt vmcnt(17)
	v_lshlrev_b32_e32 v168, 16, v190
	v_and_b32_e32 v169, 0xffff0000, v190
	v_lshlrev_b32_e32 v138, 16, v191
	v_and_b32_e32 v139, 0xffff0000, v191
	v_lshlrev_b32_e32 v170, 16, v192
	v_and_b32_e32 v171, 0xffff0000, v192
	v_lshlrev_b32_e32 v140, 16, v193
	v_and_b32_e32 v141, 0xffff0000, v193
	s_waitcnt vmcnt(16)
	v_lshlrev_b32_e32 v172, 16, v194
	v_and_b32_e32 v173, 0xffff0000, v194
	v_lshlrev_b32_e32 v144, 16, v195
	v_and_b32_e32 v145, 0xffff0000, v195
	v_lshlrev_b32_e32 v174, 16, v196
	v_and_b32_e32 v175, 0xffff0000, v196
	v_lshlrev_b32_e32 v146, 16, v197
	v_and_b32_e32 v147, 0xffff0000, v197
	s_waitcnt vmcnt(3)
	v_pk_fma_f32 v[112:113], v[112:113], v[150:151], v[138:139]
	v_pk_fma_f32 v[110:111], v[110:111], v[148:149], v[168:169]
	s_waitcnt vmcnt(2)
	v_pk_fma_f32 v[108:109], v[108:109], v[154:155], v[140:141]
	v_pk_fma_f32 v[106:107], v[106:107], v[152:153], v[170:171]
	s_waitcnt vmcnt(1)
	v_pk_fma_f32 v[104:105], v[104:105], v[158:159], v[144:145]
	v_pk_fma_f32 v[102:103], v[102:103], v[156:157], v[172:173]
	s_waitcnt vmcnt(0)
	v_pk_fma_f32 v[100:101], v[100:101], v[162:163], v[146:147]
	v_pk_fma_f32 v[98:99], v[98:99], v[160:161], v[174:175]
	v_mul_f32_e32 v137, v111, v111
	v_mul_f32_e32 v138, v113, v113
	v_mul_f32_e32 v139, v107, v107
	v_mul_f32_e32 v140, v109, v109
	v_mul_f32_e32 v141, v103, v103
	v_mul_f32_e32 v144, v105, v105
	v_mul_f32_e32 v145, v99, v99
	v_mul_f32_e32 v146, v101, v101
	v_fmac_f32_e32 v137, v110, v110
	v_fmac_f32_e32 v138, v112, v112
	v_fmac_f32_e32 v139, v106, v106
	v_fmac_f32_e32 v140, v108, v108
	v_fmac_f32_e32 v141, v102, v102
	v_fmac_f32_e32 v144, v104, v104
	v_fmac_f32_e32 v145, v98, v98
	v_fmac_f32_e32 v146, v100, v100
	v_add_f32_e32 v137, v137, v138
	v_add_f32_e32 v138, v139, v140
	v_add_f32_e32 v139, v141, v144
	v_add_f32_e32 v140, v145, v146
	v_add_f32_e32 v137, v137, v138
	v_add_f32_e32 v138, v139, v140
	v_add_f32_e32 v137, v137, v138
	ds_bpermute_b32 v138, v166, v137
	s_waitcnt lgkmcnt(0)
	v_add_f32_e32 v137, v137, v138
	ds_bpermute_b32 v138, v167, v137
	s_and_saveexec_b64 s[4:5], vcc
	s_cbranch_execz .LBB0_1159
	v_lshl_add_u32 v136, v136, 4, s3
	s_waitcnt lgkmcnt(0)
	v_add_f32_e32 v137, v137, v138
	ds_write_b32 v136, v137
.LBB0_1159:
	s_or_b64 exec, exec, s[4:5]
	v_or_b32_e32 v140, 32, v164
	v_add_u32_e32 v136, s1, v140
	v_ashrrev_i32_e32 v137, 31, v136
	s_waitcnt lgkmcnt(0)
	v_lshlrev_b64 v[138:139], 11, v[136:137]
	v_lshl_add_u64 v[138:139], s[26:27], 0, v[138:139]
	v_lshl_add_u64 v[138:139], v[130:131], 1, v[138:139]
	v_ashrrev_i32_e32 v138, 11, v136
	v_mul_i32_i24_e32 v138, 0xc00, v138
	v_ashrrev_i32_e32 v139, 31, v138
	s_mov_b64 s[4:5], 0x2000
	v_lshl_add_u64 v[138:139], v[138:139], 2, s[56:57]
	v_lshl_add_u64 v[138:139], v[138:139], 0, s[4:5]
	v_lshl_add_u64 v[156:157], v[130:131], 2, v[138:139]
	v_lshl_add_u64 v[138:139], v[142:143], 2, v[138:139]
	global_load_dwordx4 v[152:155], v[156:157], off
	s_nop 0
	global_load_dwordx4 v[156:159], v[156:157], off offset:16
	s_nop 0
	global_load_dwordx4 v[160:163], v[138:139], off
	global_load_dwordx4 v[168:171], v[138:139], off offset:16
	s_waitcnt vmcnt(5)
	v_lshlrev_b32_e32 v138, 16, v198
	v_and_b32_e32 v139, 0xffff0000, v198
	v_lshlrev_b32_e32 v144, 16, v199
	v_and_b32_e32 v145, 0xffff0000, v199
	v_lshlrev_b32_e32 v172, 16, v200
	v_and_b32_e32 v173, 0xffff0000, v200
	v_lshlrev_b32_e32 v146, 16, v201
	v_and_b32_e32 v147, 0xffff0000, v201
	s_waitcnt vmcnt(4)
	v_lshlrev_b32_e32 v174, 16, v202
	v_and_b32_e32 v175, 0xffff0000, v202
	v_lshlrev_b32_e32 v148, 16, v203
	v_and_b32_e32 v149, 0xffff0000, v203
	v_lshlrev_b32_e32 v176, 16, v204
	v_and_b32_e32 v177, 0xffff0000, v204
	v_lshlrev_b32_e32 v150, 16, v205
	v_and_b32_e32 v151, 0xffff0000, v205
	s_waitcnt vmcnt(3)
	v_pk_fma_f32 v[96:97], v[96:97], v[154:155], v[144:145]
	v_pk_fma_f32 v[138:139], v[94:95], v[152:153], v[138:139]
	s_waitcnt vmcnt(2)
	v_pk_fma_f32 v[92:93], v[92:93], v[158:159], v[146:147]
	v_pk_fma_f32 v[94:95], v[90:91], v[156:157], v[172:173]
	s_waitcnt vmcnt(1)
	v_pk_fma_f32 v[88:89], v[88:89], v[162:163], v[148:149]
	v_pk_fma_f32 v[90:91], v[86:87], v[160:161], v[174:175]
	s_waitcnt vmcnt(0)
	v_pk_fma_f32 v[84:85], v[84:85], v[170:171], v[150:151]
	v_pk_fma_f32 v[86:87], v[82:83], v[168:169], v[176:177]
	v_mul_f32_e32 v82, v139, v139
	v_mul_f32_e32 v83, v97, v97
	v_mul_f32_e32 v141, v95, v95
	v_mul_f32_e32 v144, v93, v93
	v_mul_f32_e32 v145, v91, v91
	v_mul_f32_e32 v146, v89, v89
	v_mul_f32_e32 v147, v87, v87
	v_mul_f32_e32 v148, v85, v85
	v_fmac_f32_e32 v82, v138, v138
	v_fmac_f32_e32 v83, v96, v96
	v_fmac_f32_e32 v141, v94, v94
	v_fmac_f32_e32 v144, v92, v92
	v_fmac_f32_e32 v145, v90, v90
	v_fmac_f32_e32 v146, v88, v88
	v_fmac_f32_e32 v147, v86, v86
	v_fmac_f32_e32 v148, v84, v84
	v_add_f32_e32 v82, v82, v83
	v_add_f32_e32 v83, v141, v144
	v_add_f32_e32 v141, v145, v146
	v_add_f32_e32 v144, v147, v148
	v_add_f32_e32 v82, v82, v83
	v_add_f32_e32 v83, v141, v144
	v_add_f32_e32 v82, v82, v83
	ds_bpermute_b32 v83, v166, v82
	s_waitcnt lgkmcnt(0)
	v_add_f32_e32 v82, v82, v83
	ds_bpermute_b32 v83, v167, v82
	s_and_saveexec_b64 s[8:9], vcc
	s_cbranch_execz .LBB0_1161
	v_lshl_add_u32 v140, v140, 4, s3
	s_waitcnt lgkmcnt(0)
	v_add_f32_e32 v82, v82, v83
	ds_write_b32 v140, v82
.LBB0_1161:
	s_or_b64 exec, exec, s[8:9]
	v_or_b32_e32 v140, 48, v164
	v_add_u32_e32 v82, s1, v140
	v_ashrrev_i32_e32 v141, 11, v82
	s_waitcnt lgkmcnt(0)
	v_ashrrev_i32_e32 v83, 31, v82
	v_mul_i32_i24_e32 v152, 0xc00, v141
	v_lshlrev_b64 v[144:145], 11, v[82:83]
	v_ashrrev_i32_e32 v153, 31, v152
	v_lshl_add_u64 v[144:145], s[26:27], 0, v[144:145]
	v_lshl_add_u64 v[152:153], v[152:153], 2, s[56:57]
	v_lshl_add_u64 v[148:149], v[130:131], 1, v[144:145]
	v_lshl_add_u64 v[160:161], v[152:153], 0, s[4:5]
	s_nop 0
	v_lshl_add_u64 v[156:157], v[130:131], 2, v[160:161]
	v_lshl_add_u64 v[168:169], v[142:143], 2, v[160:161]
	global_load_dwordx4 v[152:155], v[156:157], off
	s_nop 0
	global_load_dwordx4 v[156:159], v[156:157], off offset:16
	s_nop 0
	global_load_dwordx4 v[160:163], v[168:169], off
	s_nop 0
	global_load_dwordx4 v[168:171], v[168:169], off offset:16
	s_waitcnt vmcnt(5)
	v_lshlrev_b32_e32 v172, 16, v206
	v_and_b32_e32 v173, 0xffff0000, v206
	v_lshlrev_b32_e32 v144, 16, v207
	v_and_b32_e32 v145, 0xffff0000, v207
	v_lshlrev_b32_e32 v174, 16, v208
	v_and_b32_e32 v175, 0xffff0000, v208
	v_lshlrev_b32_e32 v146, 16, v209
	v_and_b32_e32 v147, 0xffff0000, v209
	s_waitcnt vmcnt(4)
	v_lshlrev_b32_e32 v176, 16, v210
	v_and_b32_e32 v177, 0xffff0000, v210
	v_lshlrev_b32_e32 v148, 16, v211
	v_and_b32_e32 v149, 0xffff0000, v211
	v_lshlrev_b32_e32 v178, 16, v212
	v_and_b32_e32 v179, 0xffff0000, v212
	v_lshlrev_b32_e32 v150, 16, v213
	v_and_b32_e32 v151, 0xffff0000, v213
	s_waitcnt vmcnt(3)
	v_pk_fma_f32 v[80:81], v[80:81], v[154:155], v[144:145]
	v_pk_fma_f32 v[78:79], v[78:79], v[152:153], v[172:173]
	s_waitcnt vmcnt(2)
	v_pk_fma_f32 v[76:77], v[76:77], v[158:159], v[146:147]
	v_pk_fma_f32 v[74:75], v[74:75], v[156:157], v[174:175]
	s_waitcnt vmcnt(1)
	v_pk_fma_f32 v[72:73], v[72:73], v[162:163], v[148:149]
	v_pk_fma_f32 v[70:71], v[70:71], v[160:161], v[176:177]
	s_waitcnt vmcnt(0)
	v_pk_fma_f32 v[68:69], v[68:69], v[170:171], v[150:151]
	v_pk_fma_f32 v[66:67], v[66:67], v[168:169], v[178:179]
	v_mul_f32_e32 v141, v79, v79
	v_mul_f32_e32 v144, v81, v81
	v_mul_f32_e32 v145, v75, v75
	v_mul_f32_e32 v146, v77, v77
	v_mul_f32_e32 v147, v71, v71
	v_mul_f32_e32 v148, v73, v73
	v_mul_f32_e32 v149, v67, v67
	v_mul_f32_e32 v150, v69, v69
	v_fmac_f32_e32 v141, v78, v78
	v_fmac_f32_e32 v144, v80, v80
	v_fmac_f32_e32 v145, v74, v74
	v_fmac_f32_e32 v146, v76, v76
	v_fmac_f32_e32 v147, v70, v70
	v_fmac_f32_e32 v148, v72, v72
	v_fmac_f32_e32 v149, v66, v66
	v_fmac_f32_e32 v150, v68, v68
	v_add_f32_e32 v141, v141, v144
	v_add_f32_e32 v144, v145, v146
	v_add_f32_e32 v145, v147, v148
	v_add_f32_e32 v146, v149, v150
	v_add_f32_e32 v141, v141, v144
	v_add_f32_e32 v144, v145, v146
	v_add_f32_e32 v141, v141, v144
	ds_bpermute_b32 v144, v166, v141
	s_waitcnt lgkmcnt(0)
	v_add_f32_e32 v141, v141, v144
	ds_bpermute_b32 v144, v167, v141
	s_and_saveexec_b64 s[4:5], vcc
	s_cbranch_execz .LBB0_1163
	v_lshl_add_u32 v140, v140, 4, s3
	s_waitcnt lgkmcnt(0)
	v_add_f32_e32 v141, v141, v144
	ds_write_b32 v140, v141
.LBB0_1163:
	s_or_b64 exec, exec, s[4:5]
	s_waitcnt lgkmcnt(0)
	v_add_u32_e32 v144, 0x80, v164
	v_add_u32_e32 v140, s1, v144
	v_ashrrev_i32_e32 v145, 11, v140
	v_ashrrev_i32_e32 v141, 31, v140
	v_mul_i32_i24_e32 v154, 0xc00, v145
	v_lshlrev_b64 v[146:147], 11, v[140:141]
	v_ashrrev_i32_e32 v155, 31, v154
	v_lshl_add_u64 v[146:147], s[26:27], 0, v[146:147]
	s_mov_b64 s[4:5], 0x2000
	v_lshl_add_u64 v[154:155], v[154:155], 2, s[56:57]
	v_lshl_add_u64 v[150:151], v[130:131], 1, v[146:147]
	v_lshl_add_u64 v[162:163], v[154:155], 0, s[4:5]
	s_nop 0
	v_lshl_add_u64 v[158:159], v[130:131], 2, v[162:163]
	v_lshl_add_u64 v[162:163], v[142:143], 2, v[162:163]
	global_load_dwordx4 v[154:157], v[158:159], off
	s_nop 0
	global_load_dwordx4 v[158:161], v[158:159], off offset:16
	s_nop 0
	global_load_dwordx4 v[168:171], v[162:163], off
	global_load_dwordx4 v[172:175], v[162:163], off offset:16
	s_waitcnt vmcnt(5)
	v_lshlrev_b32_e32 v162, 16, v214
	v_and_b32_e32 v163, 0xffff0000, v214
	v_lshlrev_b32_e32 v146, 16, v215
	v_and_b32_e32 v147, 0xffff0000, v215
	v_lshlrev_b32_e32 v176, 16, v216
	v_and_b32_e32 v177, 0xffff0000, v216
	v_lshlrev_b32_e32 v148, 16, v217
	v_and_b32_e32 v149, 0xffff0000, v217
	s_waitcnt vmcnt(4)
	v_lshlrev_b32_e32 v178, 16, v218
	v_and_b32_e32 v179, 0xffff0000, v218
	v_lshlrev_b32_e32 v150, 16, v219
	v_and_b32_e32 v151, 0xffff0000, v219
	v_lshlrev_b32_e32 v180, 16, v220
	v_and_b32_e32 v181, 0xffff0000, v220
	v_lshlrev_b32_e32 v152, 16, v221
	v_and_b32_e32 v153, 0xffff0000, v221
	s_waitcnt vmcnt(3)
	v_pk_fma_f32 v[64:65], v[64:65], v[156:157], v[146:147]
	v_pk_fma_f32 v[62:63], v[62:63], v[154:155], v[162:163]
	s_waitcnt vmcnt(2)
	v_pk_fma_f32 v[60:61], v[60:61], v[160:161], v[148:149]
	v_pk_fma_f32 v[58:59], v[58:59], v[158:159], v[176:177]
	s_waitcnt vmcnt(1)
	v_pk_fma_f32 v[56:57], v[56:57], v[170:171], v[150:151]
	v_pk_fma_f32 v[54:55], v[54:55], v[168:169], v[178:179]
	s_waitcnt vmcnt(0)
	v_pk_fma_f32 v[52:53], v[52:53], v[174:175], v[152:153]
	v_pk_fma_f32 v[50:51], v[50:51], v[172:173], v[180:181]
	v_mul_f32_e32 v145, v63, v63
	v_mul_f32_e32 v146, v65, v65
	v_mul_f32_e32 v147, v59, v59
	v_mul_f32_e32 v148, v61, v61
	v_mul_f32_e32 v149, v55, v55
	v_mul_f32_e32 v150, v57, v57
	v_mul_f32_e32 v151, v51, v51
	v_mul_f32_e32 v152, v53, v53
	v_fmac_f32_e32 v145, v62, v62
	v_fmac_f32_e32 v146, v64, v64
	v_fmac_f32_e32 v147, v58, v58
	v_fmac_f32_e32 v148, v60, v60
	v_fmac_f32_e32 v149, v54, v54
	v_fmac_f32_e32 v150, v56, v56
	v_fmac_f32_e32 v151, v50, v50
	v_fmac_f32_e32 v152, v52, v52
	v_add_f32_e32 v145, v145, v146
	v_add_f32_e32 v146, v147, v148
	v_add_f32_e32 v147, v149, v150
	v_add_f32_e32 v148, v151, v152
	v_add_f32_e32 v145, v145, v146
	v_add_f32_e32 v146, v147, v148
	v_add_f32_e32 v145, v145, v146
	ds_bpermute_b32 v146, v166, v145
	s_waitcnt lgkmcnt(0)
	v_add_f32_e32 v145, v145, v146
	ds_bpermute_b32 v146, v167, v145
	s_and_saveexec_b64 s[8:9], vcc
	s_cbranch_execz .LBB0_1165
	v_lshl_add_u32 v144, v144, 4, s3
	s_waitcnt lgkmcnt(0)
	v_add_f32_e32 v145, v145, v146
	ds_write_b32 v144, v145
.LBB0_1165:
	s_or_b64 exec, exec, s[8:9]
	s_waitcnt lgkmcnt(0)
	v_add_u32_e32 v146, 0x90, v164
	v_add_u32_e32 v144, s1, v146
	v_ashrrev_i32_e32 v147, 11, v144
	v_ashrrev_i32_e32 v145, 31, v144
	v_mul_i32_i24_e32 v156, 0xc00, v147
	v_lshlrev_b64 v[148:149], 11, v[144:145]
	v_ashrrev_i32_e32 v157, 31, v156
	v_lshl_add_u64 v[148:149], s[26:27], 0, v[148:149]
	v_lshl_add_u64 v[156:157], v[156:157], 2, s[56:57]
	v_lshl_add_u64 v[152:153], v[130:131], 1, v[148:149]
	v_lshl_add_u64 v[168:169], v[156:157], 0, s[4:5]
	s_nop 0
	v_lshl_add_u64 v[160:161], v[130:131], 2, v[168:169]
	v_lshl_add_u64 v[172:173], v[142:143], 2, v[168:169]
	global_load_dwordx4 v[156:159], v[160:161], off
	s_nop 0
	global_load_dwordx4 v[160:163], v[160:161], off offset:16
	s_nop 0
	global_load_dwordx4 v[168:171], v[172:173], off
	s_nop 0
	global_load_dwordx4 v[172:175], v[172:173], off offset:16
	s_waitcnt vmcnt(5)
	v_lshlrev_b32_e32 v176, 16, v222
	v_and_b32_e32 v177, 0xffff0000, v222
	v_lshlrev_b32_e32 v148, 16, v223
	v_and_b32_e32 v149, 0xffff0000, v223
	v_lshlrev_b32_e32 v178, 16, v224
	v_and_b32_e32 v179, 0xffff0000, v224
	v_lshlrev_b32_e32 v150, 16, v225
	v_and_b32_e32 v151, 0xffff0000, v225
	s_waitcnt vmcnt(4)
	v_lshlrev_b32_e32 v180, 16, v226
	v_and_b32_e32 v181, 0xffff0000, v226
	v_lshlrev_b32_e32 v152, 16, v227
	v_and_b32_e32 v153, 0xffff0000, v227
	v_lshlrev_b32_e32 v182, 16, v228
	v_and_b32_e32 v183, 0xffff0000, v228
	v_lshlrev_b32_e32 v154, 16, v229
	v_and_b32_e32 v155, 0xffff0000, v229
	s_waitcnt vmcnt(3)
	v_pk_fma_f32 v[48:49], v[48:49], v[158:159], v[148:149]
	v_pk_fma_f32 v[46:47], v[46:47], v[156:157], v[176:177]
	s_waitcnt vmcnt(2)
	v_pk_fma_f32 v[44:45], v[44:45], v[162:163], v[150:151]
	v_pk_fma_f32 v[42:43], v[42:43], v[160:161], v[178:179]
	s_waitcnt vmcnt(1)
	v_pk_fma_f32 v[40:41], v[40:41], v[170:171], v[152:153]
	v_pk_fma_f32 v[38:39], v[38:39], v[168:169], v[180:181]
	s_waitcnt vmcnt(0)
	v_pk_fma_f32 v[36:37], v[36:37], v[174:175], v[154:155]
	v_pk_fma_f32 v[34:35], v[34:35], v[172:173], v[182:183]
	v_mul_f32_e32 v147, v47, v47
	v_mul_f32_e32 v148, v49, v49
	v_mul_f32_e32 v149, v43, v43
	v_mul_f32_e32 v150, v45, v45
	v_mul_f32_e32 v151, v39, v39
	v_mul_f32_e32 v152, v41, v41
	v_mul_f32_e32 v153, v35, v35
	v_mul_f32_e32 v154, v37, v37
	v_fmac_f32_e32 v147, v46, v46
	v_fmac_f32_e32 v148, v48, v48
	v_fmac_f32_e32 v149, v42, v42
	v_fmac_f32_e32 v150, v44, v44
	v_fmac_f32_e32 v151, v38, v38
	v_fmac_f32_e32 v152, v40, v40
	v_fmac_f32_e32 v153, v34, v34
	v_fmac_f32_e32 v154, v36, v36
	v_add_f32_e32 v147, v147, v148
	v_add_f32_e32 v148, v149, v150
	v_add_f32_e32 v149, v151, v152
	v_add_f32_e32 v150, v153, v154
	v_add_f32_e32 v147, v147, v148
	v_add_f32_e32 v148, v149, v150
	v_add_f32_e32 v147, v147, v148
	ds_bpermute_b32 v148, v166, v147
	s_waitcnt lgkmcnt(0)
	v_add_f32_e32 v147, v147, v148
	ds_bpermute_b32 v148, v167, v147
	s_and_saveexec_b64 s[4:5], vcc
	s_cbranch_execz .LBB0_1167
	v_lshl_add_u32 v146, v146, 4, s3
	s_waitcnt lgkmcnt(0)
	v_add_f32_e32 v147, v147, v148
	ds_write_b32 v146, v147
.LBB0_1167:
	s_or_b64 exec, exec, s[4:5]
	s_waitcnt lgkmcnt(0)
	v_add_u32_e32 v148, 0xa0, v164
	v_add_u32_e32 v146, s1, v148
	v_ashrrev_i32_e32 v149, 11, v146
	v_ashrrev_i32_e32 v147, 31, v146
	v_mul_i32_i24_e32 v158, 0xc00, v149
	v_lshlrev_b64 v[150:151], 11, v[146:147]
	v_ashrrev_i32_e32 v159, 31, v158
	v_lshl_add_u64 v[150:151], s[26:27], 0, v[150:151]
	s_mov_b64 s[4:5], 0x2000
	v_lshl_add_u64 v[158:159], v[158:159], 2, s[56:57]
	v_lshl_add_u64 v[154:155], v[130:131], 1, v[150:151]
	v_lshl_add_u64 v[162:163], v[158:159], 0, s[4:5]
	s_nop 0
	v_lshl_add_u64 v[168:169], v[130:131], 2, v[162:163]
	v_lshl_add_u64 v[162:163], v[142:143], 2, v[162:163]
	global_load_dwordx4 v[158:161], v[168:169], off
	s_nop 0
	global_load_dwordx4 v[168:171], v[168:169], off offset:16
	s_nop 0
	global_load_dwordx4 v[172:175], v[162:163], off
	global_load_dwordx4 v[176:179], v[162:163], off offset:16
	s_waitcnt vmcnt(5)
	v_lshlrev_b32_e32 v162, 16, v230
	v_and_b32_e32 v163, 0xffff0000, v230
	v_lshlrev_b32_e32 v150, 16, v231
	v_and_b32_e32 v151, 0xffff0000, v231
	v_lshlrev_b32_e32 v180, 16, v232
	v_and_b32_e32 v181, 0xffff0000, v232
	v_lshlrev_b32_e32 v152, 16, v233
	v_and_b32_e32 v153, 0xffff0000, v233
	s_waitcnt vmcnt(4)
	v_lshlrev_b32_e32 v182, 16, v234
	v_and_b32_e32 v183, 0xffff0000, v234
	v_lshlrev_b32_e32 v154, 16, v235
	v_and_b32_e32 v155, 0xffff0000, v235
	v_lshlrev_b32_e32 v184, 16, v236
	v_and_b32_e32 v185, 0xffff0000, v236
	v_lshlrev_b32_e32 v156, 16, v237
	v_and_b32_e32 v157, 0xffff0000, v237
	s_waitcnt vmcnt(3)
	v_pk_fma_f32 v[32:33], v[32:33], v[160:161], v[150:151]
	v_pk_fma_f32 v[30:31], v[30:31], v[158:159], v[162:163]
	s_waitcnt vmcnt(2)
	v_pk_fma_f32 v[28:29], v[28:29], v[170:171], v[152:153]
	v_pk_fma_f32 v[26:27], v[26:27], v[168:169], v[180:181]
	s_waitcnt vmcnt(1)
	v_pk_fma_f32 v[24:25], v[24:25], v[174:175], v[154:155]
	v_pk_fma_f32 v[22:23], v[22:23], v[172:173], v[182:183]
	s_waitcnt vmcnt(0)
	v_pk_fma_f32 v[20:21], v[20:21], v[178:179], v[156:157]
	v_pk_fma_f32 v[18:19], v[18:19], v[176:177], v[184:185]
	v_mul_f32_e32 v149, v31, v31
	v_mul_f32_e32 v150, v33, v33
	v_mul_f32_e32 v151, v27, v27
	v_mul_f32_e32 v152, v29, v29
	v_mul_f32_e32 v153, v23, v23
	v_mul_f32_e32 v154, v25, v25
	v_mul_f32_e32 v155, v19, v19
	v_mul_f32_e32 v156, v21, v21
	v_fmac_f32_e32 v149, v30, v30
	v_fmac_f32_e32 v150, v32, v32
	v_fmac_f32_e32 v151, v26, v26
	v_fmac_f32_e32 v152, v28, v28
	v_fmac_f32_e32 v153, v22, v22
	v_fmac_f32_e32 v154, v24, v24
	v_fmac_f32_e32 v155, v18, v18
	v_fmac_f32_e32 v156, v20, v20
	v_add_f32_e32 v149, v149, v150
	v_add_f32_e32 v150, v151, v152
	v_add_f32_e32 v151, v153, v154
	v_add_f32_e32 v152, v155, v156
	v_add_f32_e32 v149, v149, v150
	v_add_f32_e32 v150, v151, v152
	v_add_f32_e32 v149, v149, v150
	ds_bpermute_b32 v150, v166, v149
	s_waitcnt lgkmcnt(0)
	v_add_f32_e32 v149, v149, v150
	ds_bpermute_b32 v150, v167, v149
	s_and_saveexec_b64 s[8:9], vcc
	s_cbranch_execz .LBB0_1169
	v_lshl_add_u32 v148, v148, 4, s3
	s_waitcnt lgkmcnt(0)
	v_add_f32_e32 v149, v149, v150
	ds_write_b32 v148, v149
.LBB0_1169:
	s_or_b64 exec, exec, s[8:9]
	v_add_u32_e32 v168, 0xb0, v164
	v_add_u32_e32 v148, s1, v168
	v_ashrrev_i32_e32 v158, 11, v148
	v_ashrrev_i32_e32 v149, 31, v148
	v_mul_i32_i24_e32 v158, 0xc00, v158
	s_waitcnt lgkmcnt(0)
	v_lshlrev_b64 v[150:151], 11, v[148:149]
	v_ashrrev_i32_e32 v159, 31, v158
	v_lshl_add_u64 v[150:151], s[26:27], 0, v[150:151]
	v_lshl_add_u64 v[158:159], v[158:159], 2, s[56:57]
	v_lshl_add_u64 v[154:155], v[130:131], 1, v[150:151]
	v_lshl_add_u64 v[162:163], v[158:159], 0, s[4:5]
	s_nop 0
	v_lshl_add_u64 v[170:171], v[130:131], 2, v[162:163]
	v_lshl_add_u64 v[142:143], v[142:143], 2, v[162:163]
	global_load_dwordx4 v[158:161], v[170:171], off
	s_nop 0
	global_load_dwordx4 v[170:173], v[170:171], off offset:16
	s_nop 0
	global_load_dwordx4 v[174:177], v[142:143], off
	global_load_dwordx4 v[178:181], v[142:143], off offset:16
	s_waitcnt vmcnt(5)
	v_lshlrev_b32_e32 v142, 16, v238
	v_and_b32_e32 v143, 0xffff0000, v238
	v_lshlrev_b32_e32 v150, 16, v239
	v_and_b32_e32 v151, 0xffff0000, v239
	v_lshlrev_b32_e32 v182, 16, v240
	v_and_b32_e32 v183, 0xffff0000, v240
	v_lshlrev_b32_e32 v152, 16, v241
	v_and_b32_e32 v153, 0xffff0000, v241
	s_waitcnt vmcnt(4)
	v_lshlrev_b32_e32 v184, 16, v242
	v_and_b32_e32 v185, 0xffff0000, v242
	v_lshlrev_b32_e32 v154, 16, v243
	v_and_b32_e32 v155, 0xffff0000, v243
	v_lshlrev_b32_e32 v186, 16, v244
	v_and_b32_e32 v187, 0xffff0000, v244
	v_lshlrev_b32_e32 v188, 16, v245
	v_and_b32_e32 v189, 0xffff0000, v245
	s_waitcnt vmcnt(3)
	v_pk_fma_f32 v[160:161], v[16:17], v[160:161], v[150:151]
	v_pk_fma_f32 v[162:163], v[14:15], v[158:159], v[142:143]
	s_waitcnt vmcnt(2)
	v_pk_fma_f32 v[152:153], v[12:13], v[172:173], v[152:153]
	v_pk_fma_f32 v[158:159], v[10:11], v[170:171], v[182:183]
	s_waitcnt vmcnt(1)
	v_pk_fma_f32 v[150:151], v[8:9], v[176:177], v[154:155]
	v_pk_fma_f32 v[156:157], v[6:7], v[174:175], v[184:185]
	s_waitcnt vmcnt(0)
	v_pk_fma_f32 v[142:143], v[4:5], v[180:181], v[188:189]
	v_pk_fma_f32 v[154:155], v[2:3], v[178:179], v[186:187]
	v_mul_f32_e32 v2, v163, v163
	v_mul_f32_e32 v3, v161, v161
	v_mul_f32_e32 v4, v159, v159
	v_mul_f32_e32 v5, v153, v153
	v_mul_f32_e32 v6, v157, v157
	v_mul_f32_e32 v7, v151, v151
	v_mul_f32_e32 v8, v155, v155
	v_mul_f32_e32 v9, v143, v143
	v_fmac_f32_e32 v2, v162, v162
	v_fmac_f32_e32 v3, v160, v160
	v_fmac_f32_e32 v4, v158, v158
	v_fmac_f32_e32 v5, v152, v152
	v_fmac_f32_e32 v6, v156, v156
	v_fmac_f32_e32 v7, v150, v150
	v_fmac_f32_e32 v8, v154, v154
	v_fmac_f32_e32 v9, v142, v142
	v_add_f32_e32 v2, v2, v3
	v_add_f32_e32 v3, v4, v5
	v_add_f32_e32 v4, v6, v7
	v_add_f32_e32 v5, v8, v9
	v_add_f32_e32 v2, v2, v3
	v_add_f32_e32 v3, v4, v5
	v_add_f32_e32 v2, v2, v3
	ds_bpermute_b32 v3, v166, v2
	s_waitcnt lgkmcnt(0)
	v_add_f32_e32 v2, v2, v3
	ds_bpermute_b32 v3, v167, v2
	s_and_saveexec_b64 s[4:5], vcc
	s_cbranch_execz .LBB0_1171
	v_lshl_add_u32 v4, v168, 4, s3
	s_waitcnt lgkmcnt(0)
	v_add_f32_e32 v2, v2, v3
	ds_write_b32 v4, v2

	.amdhsa_kernel _Z14fwd_megakernel4Args
		.amdhsa_group_segment_fixed_size 0
		.amdhsa_private_segment_fixed_size 0
		.amdhsa_kernarg_size 464
		.amdhsa_user_sgpr_count 2
		.amdhsa_user_sgpr_dispatch_ptr 0
		.amdhsa_user_sgpr_queue_ptr 0
		.amdhsa_user_sgpr_kernarg_segment_ptr 1
		.amdhsa_user_sgpr_dispatch_id 0
		.amdhsa_user_sgpr_kernarg_preload_length 0
		.amdhsa_user_sgpr_kernarg_preload_offset 0
		.amdhsa_user_sgpr_private_segment_size 0
		.amdhsa_uses_dynamic_stack 0
		.amdhsa_enable_private_segment 0
		.amdhsa_system_sgpr_workgroup_id_x 1
		.amdhsa_system_sgpr_workgroup_id_y 0
		.amdhsa_system_sgpr_workgroup_id_z 0
		.amdhsa_system_sgpr_workgroup_info 0
		.amdhsa_system_vgpr_workitem_id 0
		.amdhsa_next_free_vgpr 256
		.amdhsa_next_free_sgpr 102
		.amdhsa_accum_offset 256
		.amdhsa_reserve_vcc 1
		.amdhsa_float_round_mode_32 0
		.amdhsa_float_round_mode_16_64 0
		.amdhsa_float_denorm_mode_32 3
		.amdhsa_float_denorm_mode_16_64 3
		.amdhsa_dx10_clamp 1
		.amdhsa_ieee_mode 1
		.amdhsa_fp16_overflow 0
		.amdhsa_tg_split 0
		.amdhsa_exception_fp_ieee_invalid_op 0
		.amdhsa_exception_fp_denorm_src 0
		.amdhsa_exception_fp_ieee_div_zero 0
		.amdhsa_exception_fp_ieee_overflow 0
		.amdhsa_exception_fp_ieee_underflow 0
		.amdhsa_exception_fp_ieee_inexact 0
		.amdhsa_exception_int_div_zero 0
	.end_amdhsa_kernel

amdhsa.kernels:
  - .agpr_count:     0
    .args:
      - .offset:         0
        .size:           208
        .value_kind:     by_value
      - .offset:         208
        .size:           4
        .value_kind:     hidden_block_count_x
      - .offset:         212
        .size:           4
        .value_kind:     hidden_block_count_y
      - .offset:         216
        .size:           4
        .value_kind:     hidden_block_count_z
      - .offset:         220
        .size:           2
        .value_kind:     hidden_group_size_x
      - .offset:         222
        .size:           2
        .value_kind:     hidden_group_size_y
      - .offset:         224
        .size:           2
        .value_kind:     hidden_group_size_z
      - .offset:         226
        .size:           2
        .value_kind:     hidden_remainder_x
      - .offset:         228
        .size:           2
        .value_kind:     hidden_remainder_y
      - .offset:         230
        .size:           2
        .value_kind:     hidden_remainder_z
      - .offset:         248
        .size:           8
        .value_kind:     hidden_global_offset_x
      - .offset:         256
        .size:           8
        .value_kind:     hidden_global_offset_y
      - .offset:         264
        .size:           8
        .value_kind:     hidden_global_offset_z
      - .offset:         272
        .size:           2
        .value_kind:     hidden_grid_dims
      - .offset:         328
        .size:           4
        .value_kind:     hidden_dynamic_lds_size
    .group_segment_fixed_size: 0
    .kernarg_segment_align: 8
    .kernarg_segment_size: 464
    .language:       OpenCL C
    .language_version:
      - 2
      - 0
    .max_flat_workgroup_size: 512
    .name:           _Z14fwd_megakernel4Args
    .private_segment_fixed_size: 0
    .sgpr_count:     108
    .sgpr_spill_count: 97
    .symbol:         _Z14fwd_megakernel4Args.kd
    .uniform_work_group_size: 1
    .uses_dynamic_stack: false
    .vgpr_count:     256
    .vgpr_spill_count: 0
    .wavefront_size: 64
